# idx scoring: key fragment prefetch as 16 rows x 64 B per load with permlane16_swap exchange
# baseline (speedup 1.0000x reference)
; __device__ __forceinline__ void idx_unit(unsigned char* lds, const bf16_t* P, int b, int qb16, unsigned* bits) {
;     ...
;     if (tid < 128) wl[tid] = bf2f(P[(tok0 + (tid >> 3)) * PW + P_IW + (tid & 7)]) * (0.35355339059327373f * 0.125f);
;     bf16x8 aq[4][4];
; #pragma unroll
;     for (int rb = 0; rb < 4; ++rb) { const bf16_t* ap = P + (tok0 + rb * 4 + (r32 >> 3)) * PW + P_IQ + (r32 & 7) * 64 + 8 * hi;
; #pragma unroll
;         for (int kk = 0; kk < 4; ++kk) aq[rb][kk] = *(const bf16x8*)(ap + kk * 16); }
;     __syncthreads();
;     f32x4 wreg[16];
; #pragma unroll
;     for (int q = 0; q < 16; ++q) wreg[q] = *(const f32x4*)(wl + q * 8 + 4 * hi);
;     bf16x8 bk[4], bn[4];
;     { const bf16_t* kp = P + (tokb + (wid < nblk ? wid : 0) * 32 + r32) * PW + P_IK + 8 * hi;
; #pragma unroll
;       for (int kk = 0; kk < 4; ++kk) { bk[kk] = *(const bf16x8*)(kp + kk * 16); bn[kk] = bk[kk]; } }
;     for (int blk = wid; blk < nblk; blk += 8) {
;         const int key = blk * 32 + r32;
;         if (blk + 8 < nblk) { const bf16_t* kp = P + (tokb + key + 256) * PW + P_IK + 8 * hi;
.LBB0_396:
	s_or_b64 exec, exec, s[0:1]
	v_bfe_u32 v0, v182, 3, 2
	v_or_b32_e32 v3, s70, v0
	v_mov_b64_e32 v[4:5], s[46:47]
	v_mad_u64_u32 v[6:7], s[0:1], v3, s37, v[4:5]
	v_lshlrev_b32_e32 v0, 7, v182
	v_bfe_u32 v2, v182, 5, 1
	v_mad_i32_i24 v7, s71, v236, v7
	v_and_b32_e32 v0, 0x380, v0
	v_lshl_add_u64 v[6:7], v[6:7], 0, v[0:1]
	v_lshlrev_b32_e32 v8, 4, v2
	v_mov_b32_e32 v9, v1
	v_lshl_add_u64 v[6:7], v[6:7], 0, v[8:9]
	s_mov_b64 s[10:11], 0x1000
	s_movk_i32 s6, 0x1000
	v_lshl_add_u64 v[10:11], v[6:7], 0, s[10:11]
	v_add_co_u32_e32 v6, vcc, s6, v6
	s_movk_i32 s5, 0x1000
	s_nop 0
	v_addc_co_u32_e32 v7, vcc, 0, v7, vcc
	global_load_dwordx4 v[18:21], v[10:11], off offset:32
	global_load_dwordx4 v[22:25], v[10:11], off offset:64
	global_load_dwordx4 v[26:29], v[6:7], off
	global_load_dwordx4 v[30:33], v[10:11], off offset:96
	v_or_b32_e32 v6, 4, v3
	v_mad_u64_u32 v[6:7], s[0:1], v6, s37, v[4:5]
	v_mad_i32_i24 v7, s71, v236, v7
	v_lshl_add_u64 v[6:7], v[6:7], 0, v[0:1]
	v_lshl_add_u64 v[6:7], v[6:7], 0, v[8:9]
	v_lshl_add_u64 v[10:11], v[6:7], 0, s[10:11]
	v_add_co_u32_e32 v6, vcc, s6, v6
	v_and_b32_e32 v178, 31, v182
	s_nop 0
	v_addc_co_u32_e32 v7, vcc, 0, v7, vcc
	global_load_dwordx4 v[34:37], v[10:11], off offset:32
	global_load_dwordx4 v[38:41], v[10:11], off offset:64
	global_load_dwordx4 v[42:45], v[6:7], off
	global_load_dwordx4 v[46:49], v[10:11], off offset:96
	v_or_b32_e32 v6, 8, v3
	v_mad_u64_u32 v[6:7], s[0:1], v6, s37, v[4:5]
	v_mad_i32_i24 v7, s71, v236, v7
	v_or_b32_e32 v3, 12, v3
	v_lshl_add_u64 v[6:7], v[6:7], 0, v[0:1]
	v_mad_u64_u32 v[4:5], s[0:1], v3, s37, v[4:5]
	v_lshl_add_u64 v[6:7], v[6:7], 0, v[8:9]
	v_mad_i32_i24 v5, s71, v236, v5
	v_lshl_add_u64 v[10:11], v[6:7], 0, s[10:11]
	v_add_co_u32_e32 v6, vcc, s6, v6
	v_lshl_add_u64 v[4:5], v[4:5], 0, v[0:1]
	s_nop 0
	v_addc_co_u32_e32 v7, vcc, 0, v7, vcc
	v_lshl_add_u64 v[4:5], v[4:5], 0, v[8:9]
	global_load_dwordx4 v[50:53], v[10:11], off offset:32
	global_load_dwordx4 v[54:57], v[10:11], off offset:64
	global_load_dwordx4 v[58:61], v[6:7], off
	global_load_dwordx4 v[62:65], v[10:11], off offset:96
	v_lshl_add_u64 v[6:7], v[4:5], 0, s[10:11]
	v_add_co_u32_e32 v4, vcc, 0x1000, v4
	s_add_i32 s0, s8, 47
	s_nop 0
	v_addc_co_u32_e32 v5, vcc, 0, v5, vcc
	global_load_dwordx4 v[66:69], v[6:7], off offset:32
	global_load_dwordx4 v[70:73], v[6:7], off offset:64
	global_load_dwordx4 v[74:77], v[4:5], off
	global_load_dwordx4 v[78:81], v[6:7], off offset:96
	s_ashr_i32 s1, s0, 31
	s_lshr_b32 s1, s1, 27
	s_add_i32 s0, s0, s1
	s_ashr_i32 s10, s4, 6
	s_ashr_i32 s9, s0, 5
	s_cmp_ge_i32 s10, s9
	v_mov_b32_e32 v179, v1
	s_waitcnt lgkmcnt(0)
	s_barrier
	s_cbranch_scc1 .LBB0_409
	s_lshl_b32 s6, s10, 5
	s_add_i32 s0, s6, s64
	v_lshlrev_b32_e32 v0, 3, v2
	v_or_b32_e32 v3, s0, v178
	v_mov_b64_e32 v[4:5], s[46:47]
	v_mad_i64_i32 v[4:5], s[0:1], v3, s37, v[4:5]
	v_lshlrev_b32_e32 v0, 1, v0
	v_lshl_add_u64 v[4:5], v[4:5], 0, v[0:1]
	s_mov_b64 s[0:1], 0x1400
	v_lshl_add_u64 v[6:7], v[4:5], 0, s[0:1]
	v_add_co_u32_e32 v4, vcc, s5, v4
	global_load_dwordx4 v[162:165], v[6:7], off offset:96
	global_load_dwordx4 v[166:169], v[6:7], off offset:64
	global_load_dwordx4 v[170:173], v[6:7], off offset:32
	v_addc_co_u32_e32 v5, vcc, 0, v5, vcc
	global_load_dwordx4 v[174:177], v[4:5], off offset:1024
	v_lshl_add_u32 v3, v2, 4, 0
	v_add_u32_e32 v3, 0x20000, v3
	ds_read_b128 v[82:85], v3 offset:480
	ds_read_b128 v[86:89], v3 offset:448
	ds_read_b128 v[90:93], v3 offset:416
	ds_read_b128 v[94:97], v3 offset:384
	ds_read_b128 v[98:101], v3 offset:352
	ds_read_b128 v[102:105], v3 offset:320
	ds_read_b128 v[106:109], v3 offset:288
	ds_read_b128 v[110:113], v3 offset:256
	ds_read_b128 v[114:117], v3 offset:224
	ds_read_b128 v[118:121], v3 offset:192
	ds_read_b128 v[122:125], v3 offset:160
	ds_read_b128 v[126:129], v3 offset:128
	ds_read_b128 v[130:133], v3 offset:96
	ds_read_b128 v[134:137], v3 offset:64
	ds_read_b128 v[138:141], v3
	ds_read_b128 v[142:145], v3 offset:32
	s_lshl_b32 s0, s10, 6
	v_cmp_eq_u32_e64 s[4:5], 0, v2
	v_lshl_or_b32 v183, v2, 1, s8
	v_lshl_add_u32 v2, v2, 14, s0
	s_add_i32 s1, 0, 0x10000
	v_lshl_or_b32 v2, v178, 1, v2
	v_or_b32_e32 v184, 1, v183
	v_or_b32_e32 v185, 4, v183
	v_or_b32_e32 v187, 5, v183
	v_or_b32_e32 v192, 8, v183
	v_or_b32_e32 v193, 9, v183
	v_or_b32_e32 v194, 12, v183
	v_or_b32_e32 v195, 13, v183
	v_or_b32_e32 v180, s6, v178
	v_and_b32_e32 v222, 16, v178
	v_lshlrev_b32_e32 v220, 1, v222
	v_mov_b32_e32 v221, 0
	v_add_u32_e32 v196, s1, v2
	s_mov_b32 s101, 0x8000
	v_add_u32_e32 v197, 0xffff0000, v196
	s_waitcnt vmcnt(3)
	v_mov_b64_e32 v[154:155], v[162:163]
	s_waitcnt vmcnt(2)
	v_mov_b64_e32 v[146:147], v[166:167]
	s_waitcnt vmcnt(1)
	v_mov_b64_e32 v[150:151], v[170:171]
	v_mov_b64_e32 v[156:157], v[164:165]
	v_mov_b64_e32 v[148:149], v[168:169]
	s_waitcnt vmcnt(0)
	v_mov_b64_e32 v[158:159], v[174:175]
	v_mov_b64_e32 v[152:153], v[172:173]
	v_mov_b64_e32 v[160:161], v[176:177]
	s_branch .Lidx_pro

; #define IDX_TOT(j) ({ const f32x4 w4 = wreg[rb * 4 + (j)]; \
;                 const float part = w4[0] * reluf(c[4 * (j)]) + w4[1] * reluf(c[4 * (j) + 1]) + w4[2] * reluf(c[4 * (j) + 2]) + w4[3] * reluf(c[4 * (j) + 3]); swap32_add(part); })
; __device__ __forceinline__ void idx_unit(unsigned char* lds, const bf16_t* P, int b, int qb16, unsigned* bits) {
;     ...
;     for (int blk = wid; blk < nblk; blk += 8) {
;         const int key = blk * 32 + r32;
;         if (blk + 8 < nblk) { const bf16_t* kp = P + (tokb + key + 256) * PW + P_IK + 8 * hi;
; #pragma unroll
;             for (int kk = 0; kk < 4; ++kk) bn[kk] = *(const bf16x8*)(kp + kk * 16); }
; #pragma unroll
;         for (int rb = 0; rb < 4; ++rb) {
;             f32x16 c;
; #pragma unroll
;             for (int r = 0; r < 16; ++r) c[r] = 0.f;
; #pragma unroll
;             for (int kk = 0; kk < 4; ++kk) c = __builtin_amdgcn_mfma_f32_32x32x16_bf16(aq[rb][kk], bk[kk], c, 0, 0, 0);
;             asm volatile("s_nop 15\n\ts_nop 7" : "+v"(c));
;             float tq0, tq1, tq2, tq3;
;     ...
;             tq0 = IDX_TOT(0); tq1 = IDX_TOT(1); tq2 = IDX_TOT(2); tq3 = IDX_TOT(3);
;     ...
;             const float ts0 = hi ? tq2 : tq0, ts1 = hi ? tq3 : tq1;
; #pragma unroll
;             for (int jj = 0; jj < 2; ++jj) { const float tv = jj ? ts1 : ts0; const int q = rb * 4 + 2 * hi + jj;
;                 unsigned short kv = 0;
;                 if (key <= t0 + q) { const _Float16 hv = (_Float16)tv; const unsigned short hb = __builtin_bit_cast(unsigned short, hv); kv = (hb & 0x8000u) ? (unsigned short)~hb : (unsigned short)(hb | 0x8000u); }
;                 sc[q * 4096 + key] = kv; }
;         }
.LBB0_399:
	s_add_i32 s10, s10, 8
	s_cmp_ge_i32 s10, s9
	s_cselect_b64 s[0:1], -1, 0
	s_and_b64 vcc, exec, s[0:1]
	s_cbranch_vccnz .Lidx_go
	v_sub_u32_e32 v218, v180, v222
	v_ashrrev_i32_e32 v219, 31, v218
	v_lshl_add_u64 v[214:215], v[218:219], 0, s[64:65]
	v_mov_b64_e32 v[216:217], s[46:47]
	v_mad_u64_u32 v[216:217], s[6:7], v214, s37, v[216:217]
	v_mad_i32_i24 v217, v215, s37, v217
	v_lshl_add_u64 v[214:215], v[216:217], 0, v[0:1]
	v_lshl_add_u64 v[214:215], v[214:215], 0, v[220:221]
	s_mov_b64 s[6:7], 0x161400
	v_lshl_add_u64 v[216:217], v[214:215], 0, s[6:7]
	s_lshl_b32 s6, s37, 4
	s_mov_b32 s7, 0
	v_lshl_add_u64 v[224:225], v[216:217], 0, s[6:7]
	global_load_dwordx4 v[158:161], v[216:217], off
	global_load_dwordx4 v[150:153], v[224:225], off
	global_load_dwordx4 v[146:149], v[216:217], off offset:64
	global_load_dwordx4 v[154:157], v[224:225], off offset:64
.Lidx_go:
	s_waitcnt lgkmcnt(0)
	v_mfma_f32_32x32x16_bf16 v[198:213], v[42:45], v[174:177], 0
	v_max_f32_e32 v2, 0, v2
	v_max_f32_e32 v3, 0, v3
	v_max_f32_e32 v4, 0, v4
	v_max_f32_e32 v5, 0, v5
	v_max_f32_e32 v6, 0, v6
	v_max_f32_e32 v7, 0, v7
	v_max_f32_e32 v8, 0, v8
	v_max_f32_e32 v9, 0, v9
	v_mfma_f32_32x32x16_bf16 v[198:213], v[34:37], v[170:173], v[198:213]
	v_max_f32_e32 v10, 0, v10
	v_max_f32_e32 v11, 0, v11
	v_max_f32_e32 v12, 0, v12
	v_max_f32_e32 v13, 0, v13
	v_max_f32_e32 v14, 0, v14
	v_max_f32_e32 v15, 0, v15
	v_max_f32_e32 v16, 0, v16
	v_max_f32_e32 v17, 0, v17
	v_mfma_f32_32x32x16_bf16 v[198:213], v[38:41], v[166:169], v[198:213]
	v_pk_mul_f32 v[2:3], v[138:139], v[2:3]
	v_pk_mul_f32 v[6:7], v[142:143], v[6:7]
	v_pk_mul_f32 v[10:11], v[134:135], v[10:11]
	v_pk_mul_f32 v[14:15], v[130:131], v[14:15]
	v_pk_fma_f32 v[2:3], v[140:141], v[4:5], v[2:3]
	v_pk_fma_f32 v[6:7], v[144:145], v[8:9], v[6:7]
	v_pk_fma_f32 v[10:11], v[136:137], v[12:13], v[10:11]
	v_pk_fma_f32 v[14:15], v[132:133], v[16:17], v[14:15]
	v_mfma_f32_32x32x16_bf16 v[198:213], v[46:49], v[162:165], v[198:213]
	v_add_f32_e32 v3, v2, v3
	v_add_f32_e32 v7, v6, v7
	v_add_f32_e32 v11, v10, v11
	v_add_f32_e32 v15, v14, v15
	s_nop 0
	v_permlane32_swap_b32_e32 v3, v11
	s_nop 0
	v_permlane32_swap_b32_e32 v7, v15
	v_add_f32_e32 v3, v3, v11
	v_add_f32_e32 v7, v7, v15
	v_cvt_f16_f32_e32 v3, v3
	v_cvt_f16_f32_e32 v7, v7
	v_bfe_i32 v2, v3, 15, 1
	v_bfe_i32 v6, v7, 15, 1
	v_bitop3_b32 v3, v3, v2, s101 bitop3:0x1e
	v_bitop3_b32 v7, v7, v6, s101 bitop3:0x1e
	v_cmp_le_i32_e32 vcc, v180, v183
	v_cmp_le_i32_e64 s[6:7], v180, v184
	s_nop 0
	v_cndmask_b32_e32 v3, 0, v3, vcc
	v_cndmask_b32_e64 v7, 0, v7, s[6:7]
	ds_write_b16 v197, v3
	ds_write_b16 v197, v7 offset:8192
	v_mfma_f32_32x32x16_bf16 v[2:17], v[58:61], v[174:177], 0
	v_max_f32_e32 v198, 0, v198
	v_max_f32_e32 v199, 0, v199
	v_max_f32_e32 v200, 0, v200
	v_max_f32_e32 v201, 0, v201
	v_max_f32_e32 v202, 0, v202
	v_max_f32_e32 v203, 0, v203
	v_max_f32_e32 v204, 0, v204
	v_max_f32_e32 v205, 0, v205
	v_mfma_f32_32x32x16_bf16 v[2:17], v[50:53], v[170:173], v[2:17]
	v_max_f32_e32 v206, 0, v206
	v_max_f32_e32 v207, 0, v207
	v_max_f32_e32 v208, 0, v208
	v_max_f32_e32 v209, 0, v209
	v_max_f32_e32 v210, 0, v210
	v_max_f32_e32 v211, 0, v211
	v_max_f32_e32 v212, 0, v212
	v_max_f32_e32 v213, 0, v213
	v_mfma_f32_32x32x16_bf16 v[2:17], v[54:57], v[166:169], v[2:17]
	v_pk_mul_f32 v[198:199], v[126:127], v[198:199]
	v_pk_mul_f32 v[202:203], v[122:123], v[202:203]
	v_pk_mul_f32 v[206:207], v[118:119], v[206:207]
	v_pk_mul_f32 v[210:211], v[114:115], v[210:211]
	v_pk_fma_f32 v[198:199], v[128:129], v[200:201], v[198:199]
	v_pk_fma_f32 v[202:203], v[124:125], v[204:205], v[202:203]
	v_pk_fma_f32 v[206:207], v[120:121], v[208:209], v[206:207]
	v_pk_fma_f32 v[210:211], v[116:117], v[212:213], v[210:211]
	v_mfma_f32_32x32x16_bf16 v[2:17], v[62:65], v[162:165], v[2:17]
	v_add_f32_e32 v199, v198, v199
	v_add_f32_e32 v203, v202, v203
	v_add_f32_e32 v207, v206, v207
	v_add_f32_e32 v211, v210, v211
	s_nop 0
	v_permlane32_swap_b32_e32 v199, v207
	s_nop 0
	v_permlane32_swap_b32_e32 v203, v211
	v_add_f32_e32 v199, v199, v207
	v_add_f32_e32 v203, v203, v211
	v_cvt_f16_f32_e32 v199, v199
	v_cvt_f16_f32_e32 v203, v203
	v_bfe_i32 v198, v199, 15, 1
	v_bfe_i32 v202, v203, 15, 1
	v_bitop3_b32 v199, v199, v198, s101 bitop3:0x1e
	v_bitop3_b32 v203, v203, v202, s101 bitop3:0x1e
	v_cmp_le_i32_e32 vcc, v180, v185
	v_cmp_le_i32_e64 s[6:7], v180, v187
	s_nop 0
	v_cndmask_b32_e32 v199, 0, v199, vcc
	v_cndmask_b32_e64 v203, 0, v203, s[6:7]
	ds_write_b16 v197, v199 offset:32768
	ds_write_b16 v197, v203 offset:40960
	v_mfma_f32_32x32x16_bf16 v[198:213], v[74:77], v[174:177], 0
	v_max_f32_e32 v2, 0, v2
	v_max_f32_e32 v3, 0, v3
	v_max_f32_e32 v4, 0, v4
	v_max_f32_e32 v5, 0, v5
	v_max_f32_e32 v6, 0, v6
	v_max_f32_e32 v7, 0, v7
	v_max_f32_e32 v8, 0, v8
	v_max_f32_e32 v9, 0, v9
	v_mfma_f32_32x32x16_bf16 v[198:213], v[66:69], v[170:173], v[198:213]
	v_max_f32_e32 v10, 0, v10
	v_max_f32_e32 v11, 0, v11
	v_max_f32_e32 v12, 0, v12
	v_max_f32_e32 v13, 0, v13
	v_max_f32_e32 v14, 0, v14
	v_max_f32_e32 v15, 0, v15
	v_max_f32_e32 v16, 0, v16
	v_max_f32_e32 v17, 0, v17
	v_mfma_f32_32x32x16_bf16 v[198:213], v[70:73], v[166:169], v[198:213]
	v_pk_mul_f32 v[2:3], v[110:111], v[2:3]
	v_pk_mul_f32 v[6:7], v[106:107], v[6:7]
	v_pk_mul_f32 v[10:11], v[102:103], v[10:11]
	v_pk_mul_f32 v[14:15], v[98:99], v[14:15]
	v_pk_fma_f32 v[2:3], v[112:113], v[4:5], v[2:3]
	v_pk_fma_f32 v[6:7], v[108:109], v[8:9], v[6:7]
	v_pk_fma_f32 v[10:11], v[104:105], v[12:13], v[10:11]
	v_pk_fma_f32 v[14:15], v[100:101], v[16:17], v[14:15]
	v_mfma_f32_32x32x16_bf16 v[198:213], v[78:81], v[162:165], v[198:213]
	v_add_f32_e32 v3, v2, v3
	v_add_f32_e32 v7, v6, v7
	v_add_f32_e32 v11, v10, v11
	v_add_f32_e32 v15, v14, v15
	s_nop 0
	v_permlane32_swap_b32_e32 v3, v11
	s_nop 0
	v_permlane32_swap_b32_e32 v7, v15
	v_add_f32_e32 v3, v3, v11
	v_add_f32_e32 v7, v7, v15
	v_cvt_f16_f32_e32 v3, v3
	v_cvt_f16_f32_e32 v7, v7
	v_bfe_i32 v2, v3, 15, 1
	v_bfe_i32 v6, v7, 15, 1
	v_bitop3_b32 v3, v3, v2, s101 bitop3:0x1e
	v_bitop3_b32 v7, v7, v6, s101 bitop3:0x1e
	v_cmp_le_i32_e32 vcc, v180, v192
	v_cmp_le_i32_e64 s[6:7], v180, v193
	s_nop 0
	v_cndmask_b32_e32 v3, 0, v3, vcc
	v_cndmask_b32_e64 v7, 0, v7, s[6:7]
	ds_write_b16 v196, v3
	ds_write_b16 v196, v7 offset:8192
	s_waitcnt vmcnt(0)
; #define IDX_TOT(j) ({ const f32x4 w4 = wreg[rb * 4 + (j)]; \
;                 const float part = w4[0] * reluf(c[4 * (j)]) + w4[1] * reluf(c[4 * (j) + 1]) + w4[2] * reluf(c[4 * (j) + 2]) + w4[3] * reluf(c[4 * (j) + 3]); swap32_add(part); })
; __device__ __forceinline__ void idx_unit(unsigned char* lds, const bf16_t* P, int b, int qb16, unsigned* bits) {
;     ...
;         for (int rb = 0; rb < 4; ++rb) {
;             f32x16 c;
; #pragma unroll
;             for (int r = 0; r < 16; ++r) c[r] = 0.f;
; #pragma unroll
;             for (int kk = 0; kk < 4; ++kk) c = __builtin_amdgcn_mfma_f32_32x32x16_bf16(aq[rb][kk], bk[kk], c, 0, 0, 0);
;             asm volatile("s_nop 15\n\ts_nop 7" : "+v"(c));
;             float tq0, tq1, tq2, tq3;
;     ...
;             tq0 = IDX_TOT(0); tq1 = IDX_TOT(1); tq2 = IDX_TOT(2); tq3 = IDX_TOT(3);
;     ...
;             const float ts0 = hi ? tq2 : tq0, ts1 = hi ? tq3 : tq1;
; #pragma unroll
;             for (int jj = 0; jj < 2; ++jj) { const float tv = jj ? ts1 : ts0; const int q = rb * 4 + 2 * hi + jj;
;                 unsigned short kv = 0;
;                 if (key <= t0 + q) { const _Float16 hv = (_Float16)tv; const unsigned short hb = __builtin_bit_cast(unsigned short, hv); kv = (hb & 0x8000u) ? (unsigned short)~hb : (unsigned short)(hb | 0x8000u); }
;                 sc[q * 4096 + key] = kv; }
;         }
; #pragma unroll
;         for (int kk = 0; kk < 4; ++kk) bk[kk] = bn[kk];
	v_permlane16_swap_b32_e32 v158, v150
	v_permlane16_swap_b32_e32 v159, v151
	v_permlane16_swap_b32_e32 v160, v152
	v_permlane16_swap_b32_e32 v161, v153
	v_permlane16_swap_b32_e32 v146, v154
	v_permlane16_swap_b32_e32 v147, v155
	v_permlane16_swap_b32_e32 v148, v156
	v_permlane16_swap_b32_e32 v149, v157
	v_mov_b64_e32 v[162:163], v[154:155]
	v_mov_b64_e32 v[164:165], v[156:157]
	v_mov_b64_e32 v[166:167], v[146:147]
	v_mov_b64_e32 v[168:169], v[148:149]
	v_mov_b64_e32 v[170:171], v[150:151]
	v_mov_b64_e32 v[172:173], v[152:153]
	v_mov_b64_e32 v[174:175], v[158:159]
	v_mov_b64_e32 v[176:177], v[160:161]
	s_nop 1
	v_mfma_f32_32x32x16_bf16 v[2:17], v[26:29], v[174:177], 0
	v_max_f32_e32 v198, 0, v198
	v_max_f32_e32 v199, 0, v199
	v_max_f32_e32 v200, 0, v200
	v_max_f32_e32 v201, 0, v201
	v_max_f32_e32 v202, 0, v202
	v_max_f32_e32 v203, 0, v203
	v_max_f32_e32 v204, 0, v204
	v_max_f32_e32 v205, 0, v205
	v_mfma_f32_32x32x16_bf16 v[2:17], v[18:21], v[170:173], v[2:17]
	v_max_f32_e32 v206, 0, v206
	v_max_f32_e32 v207, 0, v207
	v_max_f32_e32 v208, 0, v208
	v_max_f32_e32 v209, 0, v209
	v_max_f32_e32 v210, 0, v210
	v_max_f32_e32 v211, 0, v211
	v_max_f32_e32 v212, 0, v212
	v_max_f32_e32 v213, 0, v213
	v_mfma_f32_32x32x16_bf16 v[2:17], v[22:25], v[166:169], v[2:17]
	v_pk_mul_f32 v[198:199], v[94:95], v[198:199]
	v_pk_mul_f32 v[202:203], v[90:91], v[202:203]
	v_pk_mul_f32 v[206:207], v[86:87], v[206:207]
	v_pk_mul_f32 v[210:211], v[82:83], v[210:211]
	v_pk_fma_f32 v[198:199], v[96:97], v[200:201], v[198:199]
	v_pk_fma_f32 v[202:203], v[92:93], v[204:205], v[202:203]
	v_pk_fma_f32 v[206:207], v[88:89], v[208:209], v[206:207]
	v_pk_fma_f32 v[210:211], v[84:85], v[212:213], v[210:211]
	v_mfma_f32_32x32x16_bf16 v[2:17], v[30:33], v[162:165], v[2:17]
	v_add_f32_e32 v199, v198, v199
	v_add_f32_e32 v203, v202, v203
	v_add_f32_e32 v207, v206, v207
	v_add_f32_e32 v211, v210, v211
	s_nop 0
	v_permlane32_swap_b32_e32 v199, v207
	s_nop 0
	v_permlane32_swap_b32_e32 v203, v211
	v_add_f32_e32 v199, v199, v207
	v_add_f32_e32 v203, v203, v211
	v_cvt_f16_f32_e32 v199, v199
	v_cvt_f16_f32_e32 v203, v203
	v_bfe_i32 v198, v199, 15, 1
	v_bfe_i32 v202, v203, 15, 1
	v_bitop3_b32 v199, v199, v198, s101 bitop3:0x1e
	v_bitop3_b32 v203, v203, v202, s101 bitop3:0x1e
	v_cmp_le_i32_e32 vcc, v180, v194
	v_cmp_le_i32_e64 s[6:7], v180, v195
	s_nop 0
	v_cndmask_b32_e32 v199, 0, v199, vcc
	v_cndmask_b32_e64 v203, 0, v203, s[6:7]
	ds_write_b16 v196, v199 offset:32768
	ds_write_b16 v196, v203 offset:40960
	v_add_u32_e32 v180, 0x100, v180
	v_add_u32_e32 v196, 0x200, v196
	v_add_u32_e32 v197, 0x200, v197
	s_and_b64 vcc, exec, s[0:1]
	s_cbranch_vccz .LBB0_399
